# attention selected loop micro-opts: simpler block-bit test, ones fragment kept in registers, K/V row address from a per-tile base plus SALU block offset
# speedup vs baseline: 1.0140x; 1.0140x over previous
.LBB0_1455:
	s_cmp_lt_i32 s18, 0
	s_cbranch_scc1 .LBB0_1484
	s_and_b64 s[0:1], s[16:17], exec
	v_readlane_b32 s23, v240, 47
	s_cselect_b32 s9, s23, 0
	s_add_i32 s21, 0, 0x2800
	s_add_i32 s22, 0, 0x7800
	s_and_b64 s[0:1], s[16:17], exec
	s_cselect_b32 s0, s22, s21
	v_add3_u32 v112, s0, v163, v166
	s_cselect_b32 s1, s21, s22
	s_cselect_b32 s16, 0, s23
	s_waitcnt vmcnt(0)
	v_add_u32_e32 v70, s0, v97
	s_add_u32 s0, s24, s8
	v_add_u32_e32 v66, s9, v150
	v_add_u32_e32 v67, s1, v97
	v_add_u32_e32 v68, s16, v97
	v_add_u32_e32 v69, s16, v150
	v_add3_u32 v113, s1, v163, v166
	v_add_u32_e32 v71, s9, v97
	s_addc_u32 s1, s25, 0
	v_sub_u32_e32 v111, v160, v158
	v_lshl_add_u64 v[106:107], s[0:1], 0, v[164:165]
	v_add_u32_e32 v114, v66, v171
	v_add_u32_e32 v115, v68, v96
	v_add_u32_e32 v116, v67, v96
	v_add_u32_e32 v117, v69, v171
	v_add_u32_e32 v118, v71, v96
	v_add_u32_e32 v119, v70, v96
	s_max_i32 s98, s18, 0
	s_lshr_b32 s98, s98, 3
	s_and_b32 s98, s98, 0x1ffffffc
	v_add_u32_e32 v244, s98, v157
	ds_read_b32 v242, v244 offset:16
	s_waitcnt lgkmcnt(0)
	v_mov_b32_e32 v246, s80
	v_mov_b32_e32 v247, s80
	v_mov_b32_e32 v248, s80
	v_mov_b32_e32 v249, s80
	v_mad_u64_u32 v[250:251], s[0:1], v152, s33, v[106:107]
	v_mad_i32_i24 v251, v153, s33, v251
	s_branch .LBB0_1459

.LBB0_1459:
	s_max_i32 s0, s19, 0
	s_lshl_b32 s76, s0, 6
	s_mul_i32 s98, s0, 0x30000
	s_mov_b32 s99, 0
	v_lshl_add_u64 v[70:71], v[250:251], 0, s[98:99]
	global_load_dwordx4 v[66:69], v[70:71], off offset:1024
	s_nop 0
	global_load_dwordx4 v[70:73], v[70:71], off offset:1152
	s_max_i32 s98, s7, 0
	s_lshr_b32 s98, s98, 3
	s_and_b32 s98, s98, 0x1ffffffc
	v_add_u32_e32 v244, s98, v157
	ds_read_b32 v243, v244 offset:16
	s_and_b32 s16, s18, 31
	s_mov_b32 s9, s19
	v_bfe_u32 v74, v242, s16, 1
	v_cmp_ne_u32_e32 vcc, 0, v74
	s_mov_b64 s[0:1], vcc
	s_cbranch_vccz .LBB0_1463
	ds_read_b128 v[120:123], v114
	ds_read_b128 v[124:127], v114 offset:2560
	ds_read_b128 v[128:131], v114 offset:5120
	ds_read_b128 v[132:135], v114 offset:7680
	ds_read_b128 v[136:139], v114 offset:64
	ds_read_b128 v[140:143], v114 offset:2624
	ds_read_b128 v[176:179], v114 offset:5184
	ds_read_b128 v[180:183], v114 offset:7744
	v_lshl_add_u32 v74, s18, 6, v111
	v_cvt_f32_i32_e32 v90, v74
	v_fma_f32 v74, v146, v90, -v109
	v_fma_f32 v90, v148, v90, -v110
	v_cndmask_b32_e64 v89, v173, v74, s[0:1]
	v_cndmask_b32_e64 v105, v173, v90, s[0:1]
	v_fma_f32 v74, v146, s77, v89
	v_fma_f32 v75, v146, s95, v89
	v_fma_f32 v76, v146, s4, v89
	v_fma_f32 v77, v146, s5, v89
	v_fma_f32 v78, v146, s86, v89
	v_fma_f32 v79, v146, s87, v89
	v_fma_f32 v80, v146, s84, v89
	v_fma_f32 v81, v146, s85, v89
	v_fma_f32 v82, v146, s88, v89
	v_fma_f32 v83, v146, s89, v89
	v_fma_f32 v84, v146, s90, v89
	v_fma_f32 v85, v146, s91, v89
	v_fma_f32 v86, v146, s72, v89
	v_fma_f32 v87, v146, s73, v89
	v_fma_f32 v88, v146, s74, v89
	v_fma_f32 v89, v146, s75, v89
	v_fma_f32 v90, v148, s77, v105
	v_fma_f32 v91, v148, s95, v105
	v_fma_f32 v92, v148, s4, v105
	v_fma_f32 v93, v148, s5, v105
	v_fma_f32 v94, v148, s86, v105
	v_fma_f32 v95, v148, s87, v105
	v_fma_f32 v96, v148, s84, v105
	v_fma_f32 v97, v148, s85, v105
	v_fma_f32 v98, v148, s88, v105
	v_fma_f32 v99, v148, s89, v105
	v_fma_f32 v100, v148, s90, v105
	v_fma_f32 v101, v148, s91, v105
	v_fma_f32 v102, v148, s72, v105
	v_fma_f32 v103, v148, s73, v105
	v_fma_f32 v104, v148, s74, v105
	v_fma_f32 v105, v148, s75, v105
	s_setprio 1
	s_waitcnt lgkmcnt(7)
	v_mfma_f32_16x16x32_bf16 v[74:77], v[120:123], v[6:9], v[74:77]
	v_mfma_f32_16x16x32_bf16 v[90:93], v[120:123], v[14:17], v[90:93]
	s_waitcnt lgkmcnt(6)
	v_mfma_f32_16x16x32_bf16 v[78:81], v[124:127], v[6:9], v[78:81]
	v_mfma_f32_16x16x32_bf16 v[94:97], v[124:127], v[14:17], v[94:97]
	s_waitcnt lgkmcnt(5)
	v_mfma_f32_16x16x32_bf16 v[120:123], v[128:131], v[6:9], v[82:85]
	v_mfma_f32_16x16x32_bf16 v[124:127], v[128:131], v[14:17], v[98:101]
	s_waitcnt lgkmcnt(4)
	v_mfma_f32_16x16x32_bf16 v[128:131], v[132:135], v[6:9], v[86:89]
	v_mfma_f32_16x16x32_bf16 v[132:135], v[132:135], v[14:17], v[102:105]
	s_waitcnt lgkmcnt(3)
	v_mfma_f32_16x16x32_bf16 v[102:105], v[136:139], v[2:5], v[74:77]
	v_mfma_f32_16x16x32_bf16 v[86:89], v[136:139], v[10:13], v[90:93]
	s_waitcnt lgkmcnt(2)
	v_mfma_f32_16x16x32_bf16 v[98:101], v[140:143], v[2:5], v[78:81]
	v_mfma_f32_16x16x32_bf16 v[82:85], v[140:143], v[10:13], v[94:97]
	s_waitcnt lgkmcnt(1)
	v_mfma_f32_16x16x32_bf16 v[94:97], v[176:179], v[2:5], v[120:123]
	v_mfma_f32_16x16x32_bf16 v[78:81], v[176:179], v[10:13], v[124:127]
	s_waitcnt lgkmcnt(0)
	v_mfma_f32_16x16x32_bf16 v[90:93], v[180:183], v[2:5], v[128:131]
	v_mfma_f32_16x16x32_bf16 v[74:77], v[180:183], v[10:13], v[132:135]
	s_setprio 0
	v_max3_f32 v120, v102, s96, v103
	v_max3_f32 v120, v120, v104, v105
	v_max3_f32 v120, v120, v98, v99
	v_max3_f32 v120, v120, v100, v101
	v_max3_f32 v120, v120, v94, v95
	v_max3_f32 v120, v120, v96, v97
	v_max3_f32 v120, v120, v90, v91
	v_max3_f32 v121, v120, v92, v93
	v_max3_f32 v120, v121, v86, v87
	v_max3_f32 v120, v120, v88, v89
	v_max3_f32 v120, v120, v82, v83
	v_max3_f32 v120, v120, v84, v85
	v_max3_f32 v120, v120, v78, v79
	v_max3_f32 v120, v120, v80, v81
	v_max3_f32 v120, v120, v74, v75
	v_max3_f32 v120, v120, v76, v77
	s_mov_b32 s0, 0x41000000
	v_cmp_lt_f32_e32 vcc, s0, v120
	s_cbranch_vccnz .LBB0_1482
	v_cmp_lt_f32_e32 vcc, s94, v120
	s_cbranch_vccz .LBB0_1463

.Lmy_ew1:
	v_exp_f32_e32 v98, v98
	v_exp_f32_e32 v99, v99
	v_exp_f32_e32 v100, v100
	v_exp_f32_e32 v101, v101
	v_exp_f32_e32 v82, v82
	v_exp_f32_e32 v83, v83
	v_exp_f32_e32 v84, v84
	v_exp_f32_e32 v85, v85
	v_exp_f32_e32 v86, v86
	v_exp_f32_e32 v87, v87
	v_exp_f32_e32 v88, v88
	v_exp_f32_e32 v89, v89
	v_exp_f32_e32 v122, v92
	v_exp_f32_e32 v123, v93
	v_cvt_pk_bf16_f32 v92, v98, v99
	v_cvt_pk_bf16_f32 v93, v100, v101
	v_exp_f32_e32 v78, v78
	v_exp_f32_e32 v79, v79
	v_exp_f32_e32 v80, v80
	v_exp_f32_e32 v81, v81
	v_exp_f32_e32 v98, v74
	v_exp_f32_e32 v99, v75
	v_exp_f32_e32 v100, v76
	v_cvt_pk_bf16_f32 v76, v82, v83
	ds_read_b64_tr_b16 v[82:83], v112 offset:0
	v_exp_f32_e32 v101, v77
	v_cvt_pk_bf16_f32 v77, v84, v85
	ds_read_b64_tr_b16 v[84:85], v112 offset:2560
	v_exp_f32_e32 v102, v102
	v_exp_f32_e32 v103, v103
	v_cvt_pk_bf16_f32 v74, v86, v87
	ds_read_b64_tr_b16 v[86:87], v112 offset:32
	v_exp_f32_e32 v104, v104
	v_exp_f32_e32 v105, v105
	v_cvt_pk_bf16_f32 v75, v88, v89
	ds_read_b64_tr_b16 v[88:89], v112 offset:2592
	v_exp_f32_e32 v94, v94
	v_exp_f32_e32 v95, v95
	v_exp_f32_e32 v96, v96
	v_exp_f32_e32 v97, v97
	v_exp_f32_e32 v120, v90
	v_exp_f32_e32 v121, v91
	v_cvt_pk_bf16_f32 v78, v78, v79
	v_cvt_pk_bf16_f32 v79, v80, v81
	v_cvt_pk_bf16_f32 v80, v98, v99
	ds_read_b64_tr_b16 v[98:99], v112 offset:64
	v_cvt_pk_bf16_f32 v81, v100, v101
	ds_read_b64_tr_b16 v[100:101], v112 offset:2624
	v_cvt_pk_bf16_f32 v90, v102, v103
	ds_read_b64_tr_b16 v[102:103], v112 offset:96
	v_cvt_pk_bf16_f32 v91, v104, v105
	ds_read_b64_tr_b16 v[104:105], v112 offset:2656
	v_cvt_pk_bf16_f32 v94, v94, v95
	v_cvt_pk_bf16_f32 v95, v96, v97
	v_cvt_pk_bf16_f32 v96, v120, v121
	ds_read_b64_tr_b16 v[120:121], v112 offset:5120
	v_cvt_pk_bf16_f32 v97, v122, v123
	ds_read_b64_tr_b16 v[122:123], v112 offset:7680
	ds_read_b64_tr_b16 v[124:125], v112 offset:5152
	ds_read_b64_tr_b16 v[126:127], v112 offset:7712
	ds_read_b64_tr_b16 v[128:129], v112 offset:5184
	ds_read_b64_tr_b16 v[130:131], v112 offset:7744
	ds_read_b64_tr_b16 v[132:133], v112 offset:5216
	ds_read_b64_tr_b16 v[134:135], v112 offset:7776
	s_waitcnt lgkmcnt(8)
	s_setprio 1
	v_mfma_f32_16x16x32_bf16 v[50:53], v[82:85], v[90:93], v[50:53]
	s_waitcnt lgkmcnt(0)
	v_mfma_f32_16x16x32_bf16 v[38:41], v[82:85], v[74:77], v[38:41]
	v_mfma_f32_16x16x32_bf16 v[54:57], v[86:89], v[90:93], v[54:57]
	v_mfma_f32_16x16x32_bf16 v[34:37], v[86:89], v[74:77], v[34:37]
	v_mfma_f32_16x16x32_bf16 v[46:49], v[98:101], v[90:93], v[46:49]
	v_mfma_f32_16x16x32_bf16 v[30:33], v[98:101], v[74:77], v[30:33]
	v_mfma_f32_16x16x32_bf16 v[42:45], v[102:105], v[90:93], v[42:45]
	v_mfma_f32_16x16x32_bf16 v[26:29], v[102:105], v[74:77], v[26:29]
	v_mfma_f32_16x16x32_bf16 v[62:65], v[246:249], v[90:93], v[62:65]
	v_mfma_f32_16x16x32_bf16 v[58:61], v[246:249], v[74:77], v[58:61]
	v_mfma_f32_16x16x32_bf16 v[50:53], v[120:123], v[94:97], v[50:53]
	v_mfma_f32_16x16x32_bf16 v[38:41], v[120:123], v[78:81], v[38:41]
	v_mfma_f32_16x16x32_bf16 v[54:57], v[124:127], v[94:97], v[54:57]
	v_mfma_f32_16x16x32_bf16 v[34:37], v[124:127], v[78:81], v[34:37]
	v_mfma_f32_16x16x32_bf16 v[46:49], v[128:131], v[94:97], v[46:49]
	v_mfma_f32_16x16x32_bf16 v[30:33], v[128:131], v[78:81], v[30:33]
	v_mfma_f32_16x16x32_bf16 v[42:45], v[132:135], v[94:97], v[42:45]
	v_mfma_f32_16x16x32_bf16 v[26:29], v[132:135], v[78:81], v[26:29]
	v_mfma_f32_16x16x32_bf16 v[62:65], v[246:249], v[94:97], v[62:65]
	v_mfma_f32_16x16x32_bf16 v[58:61], v[246:249], v[78:81], v[58:61]
	s_setprio 0
	s_branch .LBB0_1465

.LBB0_1470:
	s_cmp_lt_i32 s7, 0
	s_mov_b64 s[0:1], -1
	s_cbranch_scc1 .LBB0_1457
	s_max_i32 s0, s18, 0
	s_lshl_b32 s76, s0, 6
	s_mul_i32 s98, s0, 0x30000
	s_mov_b32 s99, 0
	v_lshl_add_u64 v[22:23], v[250:251], 0, s[98:99]
	global_load_dwordx4 v[18:21], v[22:23], off offset:1024
	s_nop 0
	global_load_dwordx4 v[22:25], v[22:23], off offset:1152
	s_max_i32 s98, s9, 0
	s_lshr_b32 s98, s98, 3
	s_and_b32 s98, s98, 0x1ffffffc
	v_add_u32_e32 v244, s98, v157
	ds_read_b32 v242, v244 offset:16
	s_and_b32 s16, s7, 31
	v_bfe_u32 v74, v243, s16, 1
	v_cmp_ne_u32_e32 vcc, 0, v74
	s_mov_b64 s[0:1], vcc
	s_cbranch_vccz .LBB0_1475
	ds_read_b128 v[120:123], v117
	ds_read_b128 v[124:127], v117 offset:2560
	ds_read_b128 v[128:131], v117 offset:5120
	ds_read_b128 v[132:135], v117 offset:7680
	ds_read_b128 v[136:139], v117 offset:64
	ds_read_b128 v[140:143], v117 offset:2624
	ds_read_b128 v[176:179], v117 offset:5184
	ds_read_b128 v[180:183], v117 offset:7744
	v_lshl_add_u32 v74, s7, 6, v111
	v_cvt_f32_i32_e32 v90, v74
	v_fma_f32 v74, v146, v90, -v109
	v_fma_f32 v90, v148, v90, -v110
	v_cndmask_b32_e64 v89, v173, v74, s[0:1]
	v_cndmask_b32_e64 v105, v173, v90, s[0:1]
	v_fma_f32 v74, v146, s77, v89
	v_fma_f32 v75, v146, s95, v89
	v_fma_f32 v76, v146, s4, v89
	v_fma_f32 v77, v146, s5, v89
	v_fma_f32 v78, v146, s86, v89
	v_fma_f32 v79, v146, s87, v89
	v_fma_f32 v80, v146, s84, v89
	v_fma_f32 v81, v146, s85, v89
	v_fma_f32 v82, v146, s88, v89
	v_fma_f32 v83, v146, s89, v89
	v_fma_f32 v84, v146, s90, v89
	v_fma_f32 v85, v146, s91, v89
	v_fma_f32 v86, v146, s72, v89
	v_fma_f32 v87, v146, s73, v89
	v_fma_f32 v88, v146, s74, v89
	v_fma_f32 v89, v146, s75, v89
	v_fma_f32 v90, v148, s77, v105
	v_fma_f32 v91, v148, s95, v105
	v_fma_f32 v92, v148, s4, v105
	v_fma_f32 v93, v148, s5, v105
	v_fma_f32 v94, v148, s86, v105
	v_fma_f32 v95, v148, s87, v105
	v_fma_f32 v96, v148, s84, v105
	v_fma_f32 v97, v148, s85, v105
	v_fma_f32 v98, v148, s88, v105
	v_fma_f32 v99, v148, s89, v105
	v_fma_f32 v100, v148, s90, v105
	v_fma_f32 v101, v148, s91, v105
	v_fma_f32 v102, v148, s72, v105
	v_fma_f32 v103, v148, s73, v105
	v_fma_f32 v104, v148, s74, v105
	v_fma_f32 v105, v148, s75, v105
	s_setprio 1
	s_waitcnt lgkmcnt(7)
	v_mfma_f32_16x16x32_bf16 v[74:77], v[120:123], v[6:9], v[74:77]
	v_mfma_f32_16x16x32_bf16 v[90:93], v[120:123], v[14:17], v[90:93]
	s_waitcnt lgkmcnt(6)
	v_mfma_f32_16x16x32_bf16 v[78:81], v[124:127], v[6:9], v[78:81]
	v_mfma_f32_16x16x32_bf16 v[94:97], v[124:127], v[14:17], v[94:97]
	s_waitcnt lgkmcnt(5)
	v_mfma_f32_16x16x32_bf16 v[120:123], v[128:131], v[6:9], v[82:85]
	v_mfma_f32_16x16x32_bf16 v[124:127], v[128:131], v[14:17], v[98:101]
	s_waitcnt lgkmcnt(4)
	v_mfma_f32_16x16x32_bf16 v[128:131], v[132:135], v[6:9], v[86:89]
	v_mfma_f32_16x16x32_bf16 v[132:135], v[132:135], v[14:17], v[102:105]
	s_waitcnt lgkmcnt(3)
	v_mfma_f32_16x16x32_bf16 v[102:105], v[136:139], v[2:5], v[74:77]
	v_mfma_f32_16x16x32_bf16 v[86:89], v[136:139], v[10:13], v[90:93]
	s_waitcnt lgkmcnt(2)
	v_mfma_f32_16x16x32_bf16 v[98:101], v[140:143], v[2:5], v[78:81]
	v_mfma_f32_16x16x32_bf16 v[82:85], v[140:143], v[10:13], v[94:97]
	s_waitcnt lgkmcnt(1)
	v_mfma_f32_16x16x32_bf16 v[94:97], v[176:179], v[2:5], v[120:123]
	v_mfma_f32_16x16x32_bf16 v[78:81], v[176:179], v[10:13], v[124:127]
	s_waitcnt lgkmcnt(0)
	v_mfma_f32_16x16x32_bf16 v[90:93], v[180:183], v[2:5], v[128:131]
	v_mfma_f32_16x16x32_bf16 v[74:77], v[180:183], v[10:13], v[132:135]
	s_setprio 0
	v_max3_f32 v120, v102, s96, v103
	v_max3_f32 v120, v120, v104, v105
	v_max3_f32 v120, v120, v98, v99
	v_max3_f32 v120, v120, v100, v101
	v_max3_f32 v120, v120, v94, v95
	v_max3_f32 v120, v120, v96, v97
	v_max3_f32 v120, v120, v90, v91
	v_max3_f32 v121, v120, v92, v93
	v_max3_f32 v120, v121, v86, v87
	v_max3_f32 v120, v120, v88, v89
	v_max3_f32 v120, v120, v82, v83
	v_max3_f32 v120, v120, v84, v85
	v_max3_f32 v120, v120, v78, v79
	v_max3_f32 v120, v120, v80, v81
	v_max3_f32 v120, v120, v74, v75
	v_max3_f32 v120, v120, v76, v77
	s_mov_b32 s0, 0x41000000
	v_cmp_lt_f32_e32 vcc, s0, v120
	s_cbranch_vccnz .LBB0_1483
	v_cmp_lt_f32_e32 vcc, s94, v120
	s_cbranch_vccz .LBB0_1475

.Lmy_ew2:
	v_exp_f32_e32 v98, v98
	v_exp_f32_e32 v99, v99
	v_exp_f32_e32 v100, v100
	v_exp_f32_e32 v101, v101
	v_exp_f32_e32 v82, v82
	v_exp_f32_e32 v83, v83
	v_exp_f32_e32 v84, v84
	v_exp_f32_e32 v85, v85
	v_exp_f32_e32 v86, v86
	v_exp_f32_e32 v87, v87
	v_exp_f32_e32 v88, v88
	v_exp_f32_e32 v89, v89
	v_exp_f32_e32 v122, v92
	v_exp_f32_e32 v123, v93
	v_cvt_pk_bf16_f32 v92, v98, v99
	v_cvt_pk_bf16_f32 v93, v100, v101
	v_exp_f32_e32 v78, v78
	v_exp_f32_e32 v79, v79
	v_exp_f32_e32 v80, v80
	v_exp_f32_e32 v81, v81
	v_exp_f32_e32 v98, v74
	v_exp_f32_e32 v99, v75
	v_exp_f32_e32 v100, v76
	v_cvt_pk_bf16_f32 v76, v82, v83
	ds_read_b64_tr_b16 v[82:83], v113 offset:0
	v_exp_f32_e32 v101, v77
	v_cvt_pk_bf16_f32 v77, v84, v85
	ds_read_b64_tr_b16 v[84:85], v113 offset:2560
	v_exp_f32_e32 v102, v102
	v_exp_f32_e32 v103, v103
	v_cvt_pk_bf16_f32 v74, v86, v87
	ds_read_b64_tr_b16 v[86:87], v113 offset:32
	v_exp_f32_e32 v104, v104
	v_exp_f32_e32 v105, v105
	v_cvt_pk_bf16_f32 v75, v88, v89
	ds_read_b64_tr_b16 v[88:89], v113 offset:2592
	v_exp_f32_e32 v94, v94
	v_exp_f32_e32 v95, v95
	v_exp_f32_e32 v96, v96
	v_exp_f32_e32 v97, v97
	v_exp_f32_e32 v120, v90
	v_exp_f32_e32 v121, v91
	v_cvt_pk_bf16_f32 v78, v78, v79
	v_cvt_pk_bf16_f32 v79, v80, v81
	v_cvt_pk_bf16_f32 v80, v98, v99
	ds_read_b64_tr_b16 v[98:99], v113 offset:64
	v_cvt_pk_bf16_f32 v81, v100, v101
	ds_read_b64_tr_b16 v[100:101], v113 offset:2624
	v_cvt_pk_bf16_f32 v90, v102, v103
	ds_read_b64_tr_b16 v[102:103], v113 offset:96
	v_cvt_pk_bf16_f32 v91, v104, v105
	ds_read_b64_tr_b16 v[104:105], v113 offset:2656
	v_cvt_pk_bf16_f32 v94, v94, v95
	v_cvt_pk_bf16_f32 v95, v96, v97
	v_cvt_pk_bf16_f32 v96, v120, v121
	ds_read_b64_tr_b16 v[120:121], v113 offset:5120
	v_cvt_pk_bf16_f32 v97, v122, v123
	ds_read_b64_tr_b16 v[122:123], v113 offset:7680
	ds_read_b64_tr_b16 v[124:125], v113 offset:5152
	ds_read_b64_tr_b16 v[126:127], v113 offset:7712
	ds_read_b64_tr_b16 v[128:129], v113 offset:5184
	ds_read_b64_tr_b16 v[130:131], v113 offset:7744
	ds_read_b64_tr_b16 v[132:133], v113 offset:5216
	ds_read_b64_tr_b16 v[134:135], v113 offset:7776
	s_waitcnt lgkmcnt(8)
	s_setprio 1
	v_mfma_f32_16x16x32_bf16 v[50:53], v[82:85], v[90:93], v[50:53]
	s_waitcnt lgkmcnt(0)
	v_mfma_f32_16x16x32_bf16 v[38:41], v[82:85], v[74:77], v[38:41]
	v_mfma_f32_16x16x32_bf16 v[54:57], v[86:89], v[90:93], v[54:57]
	v_mfma_f32_16x16x32_bf16 v[34:37], v[86:89], v[74:77], v[34:37]
	v_mfma_f32_16x16x32_bf16 v[46:49], v[98:101], v[90:93], v[46:49]
	v_mfma_f32_16x16x32_bf16 v[30:33], v[98:101], v[74:77], v[30:33]
	v_mfma_f32_16x16x32_bf16 v[42:45], v[102:105], v[90:93], v[42:45]
	v_mfma_f32_16x16x32_bf16 v[26:29], v[102:105], v[74:77], v[26:29]
	v_mfma_f32_16x16x32_bf16 v[62:65], v[246:249], v[90:93], v[62:65]
	v_mfma_f32_16x16x32_bf16 v[58:61], v[246:249], v[74:77], v[58:61]
	v_mfma_f32_16x16x32_bf16 v[50:53], v[120:123], v[94:97], v[50:53]
	v_mfma_f32_16x16x32_bf16 v[38:41], v[120:123], v[78:81], v[38:41]
	v_mfma_f32_16x16x32_bf16 v[54:57], v[124:127], v[94:97], v[54:57]
	v_mfma_f32_16x16x32_bf16 v[34:37], v[124:127], v[78:81], v[34:37]
	v_mfma_f32_16x16x32_bf16 v[46:49], v[128:131], v[94:97], v[46:49]
	v_mfma_f32_16x16x32_bf16 v[30:33], v[128:131], v[78:81], v[30:33]
	v_mfma_f32_16x16x32_bf16 v[42:45], v[132:135], v[94:97], v[42:45]
	v_mfma_f32_16x16x32_bf16 v[26:29], v[132:135], v[78:81], v[26:29]
	v_mfma_f32_16x16x32_bf16 v[62:65], v[246:249], v[94:97], v[62:65]
	v_mfma_f32_16x16x32_bf16 v[58:61], v[246:249], v[78:81], v[58:61]
	s_setprio 0
	s_cmp_lt_i32 s9, 0
	s_cselect_b64 s[0:1], -1, 0
	s_branch .LBB0_1477

	.amdhsa_kernel _Z6mk_fwd4Args
		.amdhsa_group_segment_fixed_size 0
		.amdhsa_private_segment_fixed_size 0
		.amdhsa_kernarg_size 536
		.amdhsa_user_sgpr_count 2
		.amdhsa_user_sgpr_dispatch_ptr 0
		.amdhsa_user_sgpr_queue_ptr 0
		.amdhsa_user_sgpr_kernarg_segment_ptr 1
		.amdhsa_user_sgpr_dispatch_id 0
		.amdhsa_user_sgpr_kernarg_preload_length 0
		.amdhsa_user_sgpr_kernarg_preload_offset 0
		.amdhsa_user_sgpr_private_segment_size 0
		.amdhsa_uses_dynamic_stack 0
		.amdhsa_enable_private_segment 0
		.amdhsa_system_sgpr_workgroup_id_x 1
		.amdhsa_system_sgpr_workgroup_id_y 0
		.amdhsa_system_sgpr_workgroup_id_z 0
		.amdhsa_system_sgpr_workgroup_info 0
		.amdhsa_system_vgpr_workitem_id 0
		.amdhsa_next_free_vgpr 252
		.amdhsa_next_free_sgpr 100
		.amdhsa_accum_offset 252
		.amdhsa_reserve_vcc 1
		.amdhsa_float_round_mode_32 0
		.amdhsa_float_round_mode_16_64 0
		.amdhsa_float_denorm_mode_32 3
		.amdhsa_float_denorm_mode_16_64 3
		.amdhsa_dx10_clamp 1
		.amdhsa_ieee_mode 1
		.amdhsa_fp16_overflow 0
		.amdhsa_tg_split 0
		.amdhsa_exception_fp_ieee_invalid_op 0
		.amdhsa_exception_fp_denorm_src 0
		.amdhsa_exception_fp_ieee_div_zero 0
		.amdhsa_exception_fp_ieee_overflow 0
		.amdhsa_exception_fp_ieee_underflow 0
		.amdhsa_exception_fp_ieee_inexact 0
		.amdhsa_exception_int_div_zero 0
	.end_amdhsa_kernel

amdhsa.kernels:
  - .agpr_count:     0
    .args:
      - .offset:         0
        .size:           280
        .value_kind:     by_value
      - .offset:         280
        .size:           4
        .value_kind:     hidden_block_count_x
      - .offset:         284
        .size:           4
        .value_kind:     hidden_block_count_y
      - .offset:         288
        .size:           4
        .value_kind:     hidden_block_count_z
      - .offset:         292
        .size:           2
        .value_kind:     hidden_group_size_x
      - .offset:         294
        .size:           2
        .value_kind:     hidden_group_size_y
      - .offset:         296
        .size:           2
        .value_kind:     hidden_group_size_z
      - .offset:         298
        .size:           2
        .value_kind:     hidden_remainder_x
      - .offset:         300
        .size:           2
        .value_kind:     hidden_remainder_y
      - .offset:         302
        .size:           2
        .value_kind:     hidden_remainder_z
      - .offset:         320
        .size:           8
        .value_kind:     hidden_global_offset_x
      - .offset:         328
        .size:           8
        .value_kind:     hidden_global_offset_y
      - .offset:         336
        .size:           8
        .value_kind:     hidden_global_offset_z
      - .offset:         344
        .size:           2
        .value_kind:     hidden_grid_dims
      - .offset:         400
        .size:           4
        .value_kind:     hidden_dynamic_lds_size
    .group_segment_fixed_size: 0
    .kernarg_segment_align: 8
    .kernarg_segment_size: 536
    .language:       OpenCL C
    .language_version:
      - 2
      - 0
    .max_flat_workgroup_size: 512
    .name:           _Z6mk_fwd4Args
    .private_segment_fixed_size: 0
    .sgpr_count:     106
    .sgpr_spill_count: 115
    .symbol:         _Z6mk_fwd4Args.kd
    .uniform_work_group_size: 1
    .uses_dynamic_stack: false
    .vgpr_count:     252
    .vgpr_spill_count: 0
    .wavefront_size: 64
